# prep: second-round items take the other part (a workgroup never runs two conv/map items)
# speedup vs baseline: 1.0581x; 1.0071x over previous
; #define BIDX bid_opaque()
; #define GDIM gdim_opaque()
; DI void prep_phase(PARAMS P, int l, int g, LAS unsigned char* lds, int wave, int lane) {
;     ...
;     for (int it = BIDX; it < 2 * nch; it += GDIM) {
;         const int cid = it >> 1, part = it & 1;
;         const int row0 = cid * 64, L = (g == 0 && cid == 136) ? 16 : 64;
;         for (int i = tid; i < 64 * 24; i += NTHREADS) { const int t = i / 24, j = i % 24; const float v = SM[(size_t)(row0 + t) * 32 + j];
;             if (j < 4) MIl[t * 4 + j] = v; else if (j < 8) MFl[t * 4 + j - 4] = v; else GAl[t * 16 + j - 8] = v; }
;         __syncthreads();
;         if (part == 0) {
.LBB0_705:
	s_or_b64 exec, exec, s[4:5]
	s_cmpk_eq_i32 s64, 0x88
	s_cselect_b64 s[2:3], -1, 0
	s_and_b64 s[90:91], s[8:9], s[2:3]
	s_and_b64 s[2:3], s[90:91], exec
	s_cselect_b32 s7, 16, 64
	s_lshr_b32 s2, s10, 8
	s_xor_b32 s2, s2, s10
	s_bitcmp1_b32 s2, 0
	s_cselect_b64 s[94:95], -1, 0
	s_mov_b64 s[4:5], -1
	s_and_b64 vcc, exec, s[94:95]
	s_waitcnt lgkmcnt(0)
	s_barrier
	s_cbranch_vccz .LBB0_717
	s_andn2_b64 vcc, exec, s[70:71]
	s_cbranch_vccnz .LBB0_716
; DI float logsig(float x) { return fminf(x, 0.f) - log1pf(__expf(-fabsf(x))); }
; DI void prep_phase(PARAMS P, int l, int g, LAS unsigned char* lds, int wave, int lane) {
;     ...
;         } else if (part == 1 && wave == 4) {
;             const int t = lane;
; #pragma unroll
;             for (int h = 0; h < 4; ++h) {
;                 float ig = MIl[t * 4 + h] + P.in[11][l * 4 + h], lf = logsig(MFl[t * 4 + h] + P.in[12][l * 4 + h]);
;                 if (t >= L) { ig = -INFINITY; lf = 0.f; }
;                 float b = lf;
; #pragma unroll
;                 for (int d = 1; d < 64; d <<= 1) { const float v = __shfl_up(b, d); if (lane >= d) b += v; }
;                 const float a = ig - b; float gm = a;
; #pragma unroll
;                 for (int d = 1; d < 64; d <<= 1) { const float v = __shfl_up(gm, d); if (lane >= d) gm = fmaxf(gm, v); }
;                 const float bl = __shfl(b, 63), mloc = bl + __shfl(gm, 63);
;                 WSTl[h * 64 + t] = __expf(a + bl - mloc);
;                 TS[(size_t)(row0 + t) * 4 + h] = (f32x4){a, gm, b, 0.f};
;                 if (lane == 0) { MCH[(cid * 4 + h) * 2] = bl; MCH[(cid * 4 + h) * 2 + 1] = mloc; }
;             }
	global_load_dword v3, v33, s[86:87]
	global_load_dword v0, v33, s[82:83]
	ds_read_b32 v4, v96
	ds_read_b32 v1, v95
	v_and_b32_e32 v2, 64, v235
	v_add_u32_e32 v5, -1, v235
	v_cmp_lt_i32_e32 vcc, v5, v2
	s_mov_b32 s2, 0x3f2aaaab
	s_lshl_b32 s16, s64, 3
	s_waitcnt vmcnt(1) lgkmcnt(1)
	v_add_f32_e32 v3, v4, v3
	v_mul_f32_e64 v4, |v3|, s15
	v_exp_f32_e32 v7, v4
	v_cndmask_b32_e32 v4, v5, v235, vcc
	v_lshlrev_b32_e32 v6, 2, v4
	v_min_f32_e32 v3, 0, v3
	v_add_f32_e32 v8, 1.0, v7
	v_add_f32_e32 v9, -1.0, v8
	v_frexp_mant_f32_e32 v10, v8
	v_cvt_f64_f32_e32 v[4:5], v8
	v_sub_f32_e32 v11, v9, v8
	v_frexp_exp_i32_f64_e32 v4, v[4:5]
	v_cmp_gt_f32_e32 vcc, s2, v10
	v_sub_f32_e32 v9, v7, v9
	v_add_f32_e32 v5, 1.0, v11
	v_subbrev_co_u32_e32 v4, vcc, 0, v4, vcc
	v_add_f32_e32 v5, v9, v5
	v_sub_u32_e32 v9, 0, v4
	v_cvt_f32_i32_e32 v4, v4
	v_ldexp_f32 v8, v8, v9
	v_ldexp_f32 v5, v5, v9
	v_add_f32_e32 v9, -1.0, v8
	v_add_f32_e32 v10, 1.0, v8
	v_add_f32_e32 v11, 1.0, v9
	v_add_f32_e32 v12, -1.0, v10
	v_sub_f32_e32 v11, v8, v11
	v_sub_f32_e32 v8, v8, v12
	v_mul_f32_e32 v12, 0x3f317218, v4
	v_add_f32_e32 v11, v5, v11
	v_add_f32_e32 v5, v5, v8
	s_mov_b32 s2, 0x3f317218
	v_fma_f32 v8, v4, s2, -v12
	v_add_f32_e32 v13, v9, v11
	v_add_f32_e32 v14, v10, v5
	v_fmac_f32_e32 v8, 0xb102e308, v4
	v_sub_f32_e32 v4, v13, v9
	v_sub_f32_e32 v9, v14, v10
	v_rcp_f32_e32 v10, v14
	v_add_f32_e32 v15, v12, v8
	v_sub_f32_e32 v5, v5, v9
	v_sub_f32_e32 v9, v15, v12
	v_sub_f32_e32 v8, v8, v9
	v_mul_f32_e32 v9, v13, v10
	v_sub_f32_e32 v4, v11, v4
	v_mul_f32_e32 v11, v14, v9
	v_fma_f32 v12, v9, v14, -v11
	v_fmac_f32_e32 v12, v9, v5
	v_add_f32_e32 v16, v11, v12
	v_sub_f32_e32 v17, v13, v16
	v_sub_f32_e32 v11, v16, v11
	v_sub_f32_e32 v13, v13, v17
	v_sub_f32_e32 v11, v11, v12
	v_sub_f32_e32 v12, v13, v16
	v_add_f32_e32 v4, v4, v12
	v_add_f32_e32 v4, v11, v4
	v_add_f32_e32 v11, v17, v4
	v_mul_f32_e32 v12, v10, v11
	v_sub_f32_e32 v13, v17, v11
	v_mul_f32_e32 v16, v14, v12
	v_add_f32_e32 v4, v4, v13
	v_add_f32_e32 v13, v9, v12
	v_fma_f32 v14, v12, v14, -v16
	v_sub_f32_e32 v9, v13, v9
	v_fmac_f32_e32 v14, v12, v5
	v_sub_f32_e32 v5, v12, v9
	v_add_f32_e32 v9, v16, v14
	v_sub_f32_e32 v12, v9, v16
	v_sub_f32_e32 v16, v11, v9
	v_sub_f32_e32 v11, v11, v16
	v_sub_f32_e32 v9, v11, v9
	v_sub_f32_e32 v12, v12, v14
	v_add_f32_e32 v4, v4, v9
	v_add_f32_e32 v4, v12, v4
	v_add_f32_e32 v4, v16, v4
	v_mul_f32_e32 v4, v10, v4
	v_add_f32_e32 v4, v5, v4
	v_add_f32_e32 v5, v13, v4
	v_mul_f32_e32 v9, v5, v5
	v_fmamk_f32 v12, v9, 0x3e9b6dac, v230
	v_sub_f32_e32 v10, v5, v13
	v_ldexp_f32 v11, v5, 1
	v_mul_f32_e32 v5, v5, v9
	v_fmaak_f32 v9, v9, v12, 0x3f2aaada
	v_mul_f32_e32 v5, v5, v9
	v_add_f32_e32 v9, v11, v5
	v_sub_f32_e32 v4, v4, v10
	v_sub_f32_e32 v10, v9, v11
	v_ldexp_f32 v4, v4, 1
	v_sub_f32_e32 v5, v5, v10
	v_add_f32_e32 v4, v4, v5
	v_add_f32_e32 v5, v9, v4
	v_sub_f32_e32 v9, v5, v9
	v_add_f32_e32 v10, v15, v5
	v_sub_f32_e32 v4, v4, v9
	v_sub_f32_e32 v9, v10, v15
	v_sub_f32_e32 v11, v10, v9
	v_sub_f32_e32 v5, v5, v9
	v_add_f32_e32 v9, v8, v4
	v_sub_f32_e32 v11, v15, v11
	v_sub_f32_e32 v12, v9, v8
	v_add_f32_e32 v5, v5, v11
	v_sub_f32_e32 v11, v9, v12
	v_sub_f32_e32 v4, v4, v12
	v_sub_f32_e32 v8, v8, v11
	v_add_f32_e32 v5, v9, v5
	v_add_f32_e32 v4, v4, v8
	v_add_f32_e32 v8, v10, v5
	v_sub_f32_e32 v9, v8, v10
	v_sub_f32_e32 v5, v5, v9
	v_add_f32_e32 v4, v4, v5
	v_add_f32_e32 v4, v8, v4
	v_cmp_neq_f32_e32 vcc, s29, v7
	s_mov_b32 s2, 0x33800000
	s_waitcnt vmcnt(0) lgkmcnt(0)
	v_add_f32_e32 v0, v1, v0
	v_cndmask_b32_e32 v4, v237, v4, vcc
	v_cmp_ngt_f32_e32 vcc, -1.0, v7
	v_lshl_or_b32 v12, v235, 2, v236
	s_nop 0
	v_cndmask_b32_e32 v4, v238, v4, vcc
	v_cmp_neq_f32_e32 vcc, -1.0, v7
	s_nop 1
	v_cndmask_b32_e32 v4, v239, v4, vcc
	v_cmp_lt_f32_e64 vcc, |v7|, s2
	s_nop 1
	v_cndmask_b32_e32 v4, v4, v7, vcc
	v_sub_f32_e32 v3, v3, v4
	v_cmp_gt_u32_e32 vcc, s7, v36
	v_add_u32_e32 v7, -2, v235
	v_cmp_lt_i32_e64 s[4:5], v7, v2
	v_cndmask_b32_e32 v4, 0, v3, vcc
	ds_bpermute_b32 v5, v6, v4
	v_cndmask_b32_e64 v7, v7, v235, s[4:5]
	v_lshlrev_b32_e32 v7, 2, v7
	v_cndmask_b32_e32 v0, v239, v0, vcc
	s_waitcnt lgkmcnt(0)
	v_add_f32_e32 v4, v4, v5
	v_cndmask_b32_e64 v3, v4, v3, s[40:41]
	ds_bpermute_b32 v4, v7, v3
	v_add_u32_e32 v5, -4, v235
	v_cmp_lt_i32_e64 s[4:5], v5, v2
	s_waitcnt lgkmcnt(0)
	v_add_f32_e32 v4, v3, v4
	v_cndmask_b32_e64 v5, v5, v235, s[4:5]
	v_lshlrev_b32_e32 v8, 2, v5
	v_cndmask_b32_e64 v3, v4, v3, s[46:47]
	ds_bpermute_b32 v4, v8, v3
	v_add_u32_e32 v5, -8, v235
	v_cmp_lt_i32_e64 s[4:5], v5, v2
	s_waitcnt lgkmcnt(0)
	v_add_f32_e32 v4, v3, v4
	v_cndmask_b32_e64 v5, v5, v235, s[4:5]
	v_lshlrev_b32_e32 v9, 2, v5
	v_cndmask_b32_e64 v3, v4, v3, s[48:49]
	ds_bpermute_b32 v4, v9, v3
	v_add_u32_e32 v5, -16, v235
	v_cmp_lt_i32_e64 s[4:5], v5, v2
	s_waitcnt lgkmcnt(0)
	v_add_f32_e32 v4, v3, v4
	v_cndmask_b32_e64 v5, v5, v235, s[4:5]
	v_lshlrev_b32_e32 v10, 2, v5
	v_cndmask_b32_e64 v3, v4, v3, s[50:51]
	ds_bpermute_b32 v4, v10, v3
	v_subrev_u32_e32 v5, 32, v235
	v_cmp_lt_i32_e64 s[4:5], v5, v2
	s_nop 1
	v_cndmask_b32_e64 v2, v5, v235, s[4:5]
	v_lshlrev_b32_e32 v11, 2, v2
	s_waitcnt lgkmcnt(0)
	v_add_f32_e32 v2, v3, v4
	v_cndmask_b32_e64 v2, v2, v3, s[52:53]
	ds_bpermute_b32 v3, v11, v2
	s_waitcnt lgkmcnt(0)
	v_add_f32_e32 v1, v2, v3
	v_cndmask_b32_e64 v32, v1, v2, s[44:45]
	v_sub_f32_e32 v30, v0, v32
	ds_bpermute_b32 v0, v6, v30
	ds_bpermute_b32 v2, v12, v32
	s_waitcnt lgkmcnt(1)
	v_max_f32_e32 v0, v0, v0
	v_max_f32_e32 v0, v30, v0
	v_cndmask_b32_e64 v0, v0, v30, s[40:41]
	ds_bpermute_b32 v1, v7, v0
	s_waitcnt lgkmcnt(0)
	v_max_f32_e32 v1, v1, v1
	v_max_f32_e32 v1, v0, v1
	v_cndmask_b32_e64 v0, v1, v0, s[46:47]
	ds_bpermute_b32 v1, v8, v0
	s_waitcnt lgkmcnt(0)
	v_max_f32_e32 v1, v1, v1
	v_max_f32_e32 v1, v0, v1
	v_cndmask_b32_e64 v0, v1, v0, s[48:49]
	ds_bpermute_b32 v1, v9, v0
	s_waitcnt lgkmcnt(0)
	v_max_f32_e32 v1, v1, v1
	v_max_f32_e32 v1, v0, v1
	v_cndmask_b32_e64 v0, v1, v0, s[50:51]
	ds_bpermute_b32 v1, v10, v0
	s_waitcnt lgkmcnt(0)
	v_max_f32_e32 v1, v1, v1
	v_max_f32_e32 v1, v0, v1
	v_cndmask_b32_e64 v0, v1, v0, s[52:53]
	ds_bpermute_b32 v1, v11, v0
	v_max_f32_e32 v3, v0, v0
	s_waitcnt lgkmcnt(0)
	v_max_f32_e32 v1, v1, v1
	v_max_f32_e32 v1, v3, v1
	v_cndmask_b32_e64 v3, v1, v0, s[44:45]
	ds_bpermute_b32 v31, v12, v3
	v_or_b32_e32 v0, s6, v36
	v_ashrrev_i32_e32 v1, 31, v0
	v_lshlrev_b64 v[0:1], 6, v[0:1]
	v_lshl_add_u64 v[0:1], s[66:67], 0, v[0:1]
	s_waitcnt lgkmcnt(0)
	v_pk_add_f32 v[4:5], v[30:31], v[2:3] op_sel_hi:[1,0]
	v_mov_b32_e32 v31, v3
	v_sub_f32_e32 v4, v4, v5
	v_mul_f32_e32 v4, 0x3fb8aa3b, v4
	v_exp_f32_e32 v4, v4
	global_store_dwordx4 v[0:1], v[30:33], off
	ds_write_b32 v37, v4
	s_and_saveexec_b64 s[4:5], s[40:41]
	s_cbranch_execz .LBB0_709
	s_ashr_i32 s17, s16, 31
	s_lshl_b64 s[2:3], s[16:17], 2
	s_add_u32 s2, s36, s2
	s_addc_u32 s3, s37, s3
	v_mov_b32_e32 v3, v5
	global_store_dwordx2 v33, v[2:3], s[2:3]

; DI float bf2f(bf16_t v) { return __uint_as_float((unsigned)v << 16); }
; DI bf16_t f2bf(float f) { return (bf16_t)cvt_pk_bf16(f, 0.f); }
; DI float silu(float x) { return x * sigm(x); }
; DI void prep_phase(PARAMS P, int l, int g, LAS unsigned char* lds, int wave, int lane) {
;     ...
; #pragma unroll 1
;             for (int t0 = 0; t0 < 64; t0 += 8) {
;                 bf16_t xr[8];
; #pragma unroll
;                 for (int j = 0; j < 8; ++j) xr[j] = mx[(size_t)(row0 + t0 + j) * 512 + ch];
; #pragma unroll
;                 for (int j = 0; j < 8; ++j) { const int t = t0 + j; const bf16_t xb = xr[j]; const float x = bf2f(xb);
;                     const float cv = silu(cb + w0 * x3 + w1 * x2 + w2 * x1 + w3 * x); const bf16_t cbf = f2bf(cv);
;                     Cl[t * 520 + ch] = cbf; Xl[t * 520 + ch] = xb; cc[(size_t)(row0 + t) * 512 + ch] = cbf;
;                     x3 = x2; x2 = x1; x1 = x; }
;             }
.LBB0_736:
	s_ashr_i32 s7, s6, 31
	s_lshl_b64 s[2:3], s[6:7], 10
	v_lshl_add_u64 v[0:1], v[84:85], 0, s[2:3]
	s_mov_b32 s2, -8
	v_mov_b32_e32 v9, v121
	v_add_co_u32_e32 v178, vcc, 0xf9b5f000, v0
	s_nop 1
	v_addc_co_u32_e32 v179, vcc, -1, v1, vcc
	v_add_co_u32_e32 v180, vcc, 0xf9b60000, v0
	s_nop 1
	v_addc_co_u32_e32 v181, vcc, -1, v1, vcc
	global_load_ushort v170, v[178:179], off offset:-3072
	global_load_ushort v171, v[178:179], off offset:-2048
	global_load_ushort v172, v[178:179], off offset:-1024
	global_load_ushort v173, v[178:179], off
	global_load_ushort v174, v[180:181], off offset:-3072
	global_load_ushort v175, v[180:181], off offset:-2048
	global_load_ushort v176, v[180:181], off offset:-1024
	global_load_ushort v177, v[180:181], off
	s_waitcnt vmcnt(0)
	s_branch .Lconv_in
.LBB0_737:
	s_waitcnt vmcnt(8)
.Lconv_in:
	v_mov_b32_e32 v13, v170
	v_mov_b32_e32 v16, v171
	v_mov_b32_e32 v17, v172
	v_mov_b32_e32 v18, v173
	v_mov_b32_e32 v19, v174
	v_mov_b32_e32 v20, v175
	v_mov_b32_e32 v11, v176
	v_mov_b32_e32 v10, v177
	v_add_co_u32_e32 v178, vcc, 0xf9b61000, v0
	s_nop 1
	v_addc_co_u32_e32 v179, vcc, -1, v1, vcc
	v_add_co_u32_e32 v180, vcc, 0xf9b62000, v0
	s_nop 1
	v_addc_co_u32_e32 v181, vcc, -1, v1, vcc
	global_load_ushort v170, v[178:179], off offset:-3072
	global_load_ushort v171, v[178:179], off offset:-2048
	global_load_ushort v172, v[178:179], off offset:-1024
	global_load_ushort v173, v[178:179], off
	global_load_ushort v174, v[180:181], off offset:-3072
	global_load_ushort v175, v[180:181], off offset:-2048
	global_load_ushort v176, v[180:181], off offset:-1024
	global_load_ushort v177, v[180:181], off
	v_fma_f32 v2, v4, v2, v8
	v_fmac_f32_e32 v2, v5, v3
	s_nop 0
	v_fmac_f32_e32 v2, v6, v12
	s_movk_i32 s3, 0xf000
	v_fma_f32 v3, v4, v3, v8
	v_fmac_f32_e32 v3, v5, v12
	v_fma_f32 v12, v4, v12, v8
	s_add_i32 s2, s2, 8
	s_cmp_lt_u32 s2, 56
	v_lshlrev_b32_e32 v21, 16, v13
	v_fmac_f32_e32 v2, v7, v21
	v_mul_f32_e32 v14, 0xbfb8aa3b, v2
	v_exp_f32_e32 v14, v14
	v_fmac_f32_e32 v3, v6, v21
	v_fmac_f32_e32 v12, v5, v21
	v_add_f32_e32 v14, 1.0, v14
	v_rcp_f32_e32 v14, v14
	s_nop 0
	v_mul_f32_e32 v2, v2, v14
	v_cvt_pk_bf16_f32 v2, v2, s0
	v_add_u32_e32 v14, 0xfffefc00, v9
	ds_write_b16 v14, v2
	ds_write_b16 v9, v13
	v_add_co_u32_e32 v14, vcc, s3, v0
	s_nop 1
	v_addc_co_u32_e32 v15, vcc, -1, v1, vcc
	global_store_short v[14:15], v2, off offset:-3072
	v_lshlrev_b32_e32 v2, 16, v16
	v_fmac_f32_e32 v3, v7, v2
	v_mul_f32_e32 v13, 0xbfb8aa3b, v3
	v_exp_f32_e32 v13, v13
	v_fmac_f32_e32 v12, v6, v2
	v_add_f32_e32 v13, 1.0, v13
	v_rcp_f32_e32 v13, v13
	s_nop 0
	v_mul_f32_e32 v3, v3, v13
	v_cvt_pk_bf16_f32 v3, v3, s0
	v_add_u32_e32 v13, 0xffff0010, v9
	ds_write_b16 v13, v3
	ds_write_b16 v9, v16 offset:1040
	global_store_short v[14:15], v3, off offset:-2048
	v_lshlrev_b32_e32 v3, 16, v17
	v_fmac_f32_e32 v12, v7, v3
	v_mul_f32_e32 v13, 0xbfb8aa3b, v12
	v_exp_f32_e32 v13, v13
	s_nop 0
	v_add_f32_e32 v13, 1.0, v13
	v_rcp_f32_e32 v13, v13
	s_nop 0
	v_mul_f32_e32 v12, v12, v13
	v_cvt_pk_bf16_f32 v12, v12, s0
	v_add_u32_e32 v13, 0xffff0420, v9
	ds_write_b16 v13, v12
	ds_write_b16 v9, v17 offset:2080
	v_fma_f32 v13, v4, v21, v8
	v_fmac_f32_e32 v13, v5, v2
	global_store_short v[14:15], v12, off offset:-1024
	v_lshlrev_b32_e32 v12, 16, v18
	v_fmac_f32_e32 v13, v6, v3
	v_fmac_f32_e32 v13, v7, v12
	v_mul_f32_e32 v14, 0xbfb8aa3b, v13
	v_exp_f32_e32 v14, v14
	v_fma_f32 v2, v4, v2, v8
	v_fmac_f32_e32 v2, v5, v3
	v_fmac_f32_e32 v2, v6, v12
	v_add_f32_e32 v14, 1.0, v14
	v_rcp_f32_e32 v14, v14
	v_add_u32_e32 v15, 0xffff1050, v9
	v_mul_f32_e32 v13, v13, v14
	v_cvt_pk_bf16_f32 v13, v13, s0
	v_add_u32_e32 v14, 0xffff0830, v9
	ds_write_b16 v14, v13
	ds_write_b16 v9, v18 offset:3120
	global_store_short v[0:1], v13, off offset:-4096
	v_lshlrev_b32_e32 v13, 16, v19
	v_fmac_f32_e32 v2, v7, v13
	v_mul_f32_e32 v14, 0xbfb8aa3b, v2
	v_exp_f32_e32 v14, v14
	s_nop 0
	v_add_f32_e32 v14, 1.0, v14
	v_rcp_f32_e32 v14, v14
	s_nop 0
	v_mul_f32_e32 v2, v2, v14
	v_cvt_pk_bf16_f32 v2, v2, s0
	v_add_u32_e32 v14, 0xffff0c40, v9
	ds_write_b16 v14, v2
	ds_write_b16 v9, v19 offset:4160
	v_fma_f32 v14, v4, v3, v8
	v_fmac_f32_e32 v14, v5, v12
	global_store_short v[0:1], v2, off offset:-3072
	v_fmac_f32_e32 v14, v6, v13
	v_lshlrev_b32_e32 v2, 16, v20
	v_fmac_f32_e32 v14, v7, v2
	v_mul_f32_e32 v16, 0xbfb8aa3b, v14
	v_exp_f32_e32 v16, v16
	v_fma_f32 v12, v4, v12, v8
	v_fmac_f32_e32 v12, v5, v13
	v_lshlrev_b32_e32 v3, 16, v11
	v_add_f32_e32 v16, 1.0, v16
	v_rcp_f32_e32 v16, v16
	v_fmac_f32_e32 v12, v6, v2
	v_fmac_f32_e32 v12, v7, v3
	ds_write_b16 v9, v20 offset:5200
	v_mul_f32_e32 v14, v14, v16
	v_cvt_pk_bf16_f32 v14, v14, s0
	ds_write_b16 v15, v14
	global_store_short v[0:1], v14, off offset:-2048
	v_mul_f32_e32 v14, 0xbfb8aa3b, v12
	v_exp_f32_e32 v14, v14
	s_nop 0
	v_add_f32_e32 v14, 1.0, v14
	v_rcp_f32_e32 v14, v14
	s_nop 0
	v_mul_f32_e32 v12, v12, v14
	v_cvt_pk_bf16_f32 v12, v12, s0
	v_add_u32_e32 v14, 0xffff1460, v9
	ds_write_b16 v14, v12
	ds_write_b16 v9, v11 offset:6240
	v_fma_f32 v11, v4, v13, v8
	v_fmac_f32_e32 v11, v5, v2
	global_store_short v[0:1], v12, off offset:-1024
	v_lshlrev_b32_e32 v12, 16, v10
	v_fmac_f32_e32 v11, v6, v3
	v_fmac_f32_e32 v11, v7, v12
	v_mul_f32_e32 v13, 0xbfb8aa3b, v11
	v_exp_f32_e32 v13, v13
	s_nop 0
	v_add_f32_e32 v13, 1.0, v13
	v_rcp_f32_e32 v13, v13
	s_nop 0
	v_mul_f32_e32 v11, v11, v13
	v_cvt_pk_bf16_f32 v11, v11, s0
	v_add_u32_e32 v13, 0xffff1870, v9
	ds_write_b16 v13, v11
	ds_write_b16 v9, v10 offset:7280
	global_store_short v[0:1], v11, off
	v_lshl_add_u64 v[0:1], v[0:1], 0, s[88:89]
	v_add_u32_e32 v9, 0x2080, v9
	s_cbranch_scc1 .LBB0_737
	s_and_b64 vcc, exec, s[16:17]
	s_cbranch_vccz .LBB0_751
	s_and_b32 s2, s10, 62
	s_cmp_eq_u32 s2, 62
	s_cselect_b64 s[2:3], -1, 0
	s_and_b64 s[2:3], s[2:3], s[4:5]
	s_mov_b64 s[16:17], 0
	s_and_b64 vcc, exec, s[2:3]
	s_mov_b64 s[4:5], 0
	s_cbranch_vccnz .LBB0_752
	s_mov_b64 s[20:21], 0x8e10200
	s_and_b64 vcc, exec, s[16:17]
	s_cbranch_vccnz .LBB0_753
